# grid barrier poll loop: two staggered polls in flight with s_sleep 10 spacing (fewer, better-spaced polls of the top counter)
# speedup vs baseline: 1.0093x; 1.0048x over previous
.Lgb0_spin:
	global_load_dword v1, v5, s[10:11] sc1
	s_sleep 10
.Lgb0_spin2:
	global_load_dword v3, v5, s[10:11] sc1
	s_waitcnt vmcnt(1)
	v_readfirstlane_b32 s9, v1
	s_sub_i32 s9, s9, s8
	s_cmp_ge_i32 s9, 0
	s_cbranch_scc1 .Lgb0_done
	s_sleep 10
	global_load_dword v1, v5, s[10:11] sc1
	s_waitcnt vmcnt(1)
	v_readfirstlane_b32 s9, v3
	s_sub_i32 s9, s9, s8
	s_cmp_ge_i32 s9, 0
	s_cbranch_scc1 .Lgb0_done
	s_sleep 10
	s_add_i32 s12, s12, 1
	s_cmp_lt_u32 s12, 0x80000
	s_cbranch_scc1 .Lgb0_spin2
